# speedup vs baseline: 1.0105x; 1.0105x over previous
; __device__ __forceinline__ void gemm_stage(const Params& p, int s, char* smem, const int wv) {
;     ...
;     if (s == 0) {
;       if (t < 2560) {
;         tile_map(t, 40, 64, pm, pn);
;         td.A = (const u16*)(ws + OFF_WT0I) + (long)pm * 256 * 4096; td.B = H + (long)pn * 256 * 4096;
;         td.mode = pm >= 24 ? EPI_SILU : EPI_PLAIN; td.outb = (u16*)(ws + OFF_PB0); td.ldo = LD0;
.LBB0_252:
	s_andn2_b64 vcc, exec, s[26:27]
	s_cbranch_vccnz .LBB0_254
	s_lshr_b32 s0, s51, 3
	s_lshr_b32 s30, s0, 3
	s_and_b32 s0, s0, 7
	s_and_b32 s12, s51, 7
	s_lshl_b32 s12, s12, 3
	s_or_b32 s12, s12, s0
	s_mov_b32 s31, 0
	s_lshl_b64 s[0:1], s[30:31], 21
	s_add_u32 s0, s96, s0
	s_addc_u32 s1, s97, s1
	s_bfe_i64 s[26:27], s[12:13], 0x100000
	s_lshl_b64 s[26:27], s[26:27], 21
	v_readlane_b32 s28, v255, 16
	s_add_u32 s36, s28, s26
	v_readlane_b32 s26, v255, 17
	s_addc_u32 s37, s26, s27
	s_cmp_lt_i32 s30, 24
	s_cselect_b64 s[34:35], -1, 0
	s_lshl_b32 s31, s12, 8
	s_mov_b64 s[28:29], 0x2800
	s_mov_b64 s[26:27], s[4:5]
	s_branch .LBB0_255
